# PEER gather: next token's H row prefetched by LDS-DMA into a per-wave slot (placement phases of hot loops preserved)
# baseline (speedup 1.0000x reference)
.Lhpf_done:
	v_mov_b32_e32 v0, v16
	v_lshl_add_u32 v10, v17, 4, v216
	v_and_b32_e32 v158, 15, v17
	s_add_u32 s10, s36, s20
	s_addc_u32 s11, s37, s21
	s_add_u32 s12, s10, 0x9a04000
	s_addc_u32 s13, s11, 0
	v_and_b32_e32 v152, -16, v17
	v_ashrrev_i32_e32 v153, 31, v152
	v_lshlrev_b32_e32 v224, 3, v17
	v_and_b32_e32 v154, 3, v17
	s_mov_b64 s[0:1], 0xda04000
	s_waitcnt vmcnt(3)
	v_lshlrev_b32_e32 v53, 16, v2
	v_and_b32_e32 v55, 0xffff0000, v2
	v_lshlrev_b32_e32 v57, 16, v3
	s_waitcnt vmcnt(0)
	v_lshlrev_b32_e32 v1, 16, v22
	v_and_b32_e32 v13, 0xffff0000, v22
	v_mul_f32_e32 v11, 0x3e800000, v1
	v_mul_f32_e32 v14, 0x3e800000, v13
	v_lshlrev_b32_e32 v15, 16, v23
	v_and_b32_e32 v23, 0xffff0000, v23
	v_mul_f32_e32 v22, 0x3e800000, v15
	v_mul_f32_e32 v26, 0x3e800000, v23
	v_lshlrev_b32_e32 v27, 16, v24
	v_and_b32_e32 v24, 0xffff0000, v24
	v_cvt_scalef32_pk_fp4_f32 v0, v11, v14, 1.0
	v_mul_f32_e32 v28, 0x3e800000, v27
	v_mul_f32_e32 v29, 0x3e800000, v24
	v_lshlrev_b32_e32 v30, 16, v25
	v_and_b32_e32 v25, 0xffff0000, v25
	v_cvt_scalef32_pk_fp4_f32 v0, v22, v26, 1.0 op_sel:[0,0,1,0]
	v_mul_f32_e32 v31, 0x3e800000, v30
	v_mul_f32_e32 v32, 0x3e800000, v25
	v_cvt_scalef32_pk_fp4_f32 v0, v28, v29, 1.0 op_sel:[0,0,0,1]
	v_lshlrev_b32_e32 v11, 16, v18
	v_cvt_scalef32_pk_fp4_f32 v0, v31, v32, 1.0 op_sel:[0,0,1,1]
	v_and_b32_e32 v18, 0xffff0000, v18
	v_and_b32_e32 v59, 0xffff0000, v3
	v_cvt_scalef32_pk_f32_fp4 v[2:3], v0, 1.0
	v_mul_f32_e32 v14, 0x3e800000, v11
	v_mul_f32_e32 v22, 0x3e800000, v18
	v_lshlrev_b32_e32 v26, 16, v19
	v_and_b32_e32 v19, 0xffff0000, v19
	v_fma_f32 v69, v1, s87, -v2
	v_mov_b32_e32 v1, v16
	v_mul_f32_e32 v28, 0x3e800000, v26
	v_mul_f32_e32 v29, 0x3e800000, v19
	v_lshlrev_b32_e32 v31, 16, v20
	v_and_b32_e32 v20, 0xffff0000, v20
	v_cvt_scalef32_pk_fp4_f32 v1, v14, v22, 1.0
	v_mul_f32_e32 v32, 0x3e800000, v31
	v_mul_f32_e32 v33, 0x3e800000, v20
	v_lshlrev_b32_e32 v34, 16, v21
	v_and_b32_e32 v21, 0xffff0000, v21
	v_cvt_scalef32_pk_fp4_f32 v1, v28, v29, 1.0 op_sel:[0,0,1,0]
	v_mul_f32_e32 v35, 0x3e800000, v34
	v_mul_f32_e32 v36, 0x3e800000, v21
	v_cvt_scalef32_pk_fp4_f32 v1, v32, v33, 1.0 op_sel:[0,0,0,1]
	v_lshlrev_b32_e32 v37, 16, v6
	v_cvt_scalef32_pk_fp4_f32 v1, v35, v36, 1.0 op_sel:[0,0,1,1]
	v_and_b32_e32 v39, 0xffff0000, v6
	v_fma_f32 v13, v13, s87, -v3
	v_cvt_scalef32_pk_f32_fp4 v[2:3], v1, 1.0
	v_mul_f32_e32 v38, 0x3e800000, v37
	v_mul_f32_e32 v40, 0x3e800000, v39
	v_lshlrev_b32_e32 v41, 16, v7
	v_and_b32_e32 v43, 0xffff0000, v7
	v_mul_f32_e32 v54, 0x3e800000, v53
	v_mul_f32_e32 v56, 0x3e800000, v55
	v_fma_f32 v11, v11, s87, -v2
	v_fma_f32 v18, v18, s87, -v3
	v_mov_b32_e32 v2, v16
	v_mov_b32_e32 v3, v16
	v_mul_f32_e32 v42, 0x3e800000, v41
	v_mul_f32_e32 v44, 0x3e800000, v43
	v_lshlrev_b32_e32 v45, 16, v8
	v_and_b32_e32 v47, 0xffff0000, v8
	v_mul_f32_e32 v58, 0x3e800000, v57
	v_mul_f32_e32 v60, 0x3e800000, v59
	v_lshlrev_b32_e32 v61, 16, v4
	v_and_b32_e32 v63, 0xffff0000, v4
	v_cvt_scalef32_pk_fp4_f32 v2, v38, v40, 1.0
	v_cvt_scalef32_pk_fp4_f32 v3, v54, v56, 1.0
	v_mul_f32_e32 v46, 0x3e800000, v45
	v_mul_f32_e32 v48, 0x3e800000, v47
	v_lshlrev_b32_e32 v49, 16, v9
	v_and_b32_e32 v51, 0xffff0000, v9
	v_mul_f32_e32 v62, 0x3e800000, v61
	v_mul_f32_e32 v64, 0x3e800000, v63
	v_lshlrev_b32_e32 v65, 16, v5
	v_and_b32_e32 v67, 0xffff0000, v5
	v_cvt_scalef32_pk_fp4_f32 v2, v42, v44, 1.0 op_sel:[0,0,1,0]
	v_cvt_scalef32_pk_fp4_f32 v3, v58, v60, 1.0 op_sel:[0,0,1,0]
	v_mul_f32_e32 v50, 0x3e800000, v49
	v_mul_f32_e32 v52, 0x3e800000, v51
	v_mul_f32_e32 v66, 0x3e800000, v65
	v_mul_f32_e32 v68, 0x3e800000, v67
	v_cvt_scalef32_pk_fp4_f32 v2, v46, v48, 1.0 op_sel:[0,0,0,1]
	v_cvt_scalef32_pk_fp4_f32 v3, v62, v64, 1.0 op_sel:[0,0,0,1]
	v_cvt_scalef32_pk_f32_fp4 v[4:5], v0, 1.0 op_sel:[1,0,0]
	v_cvt_scalef32_pk_fp4_f32 v2, v50, v52, 1.0 op_sel:[0,0,1,1]
	v_cvt_scalef32_pk_fp4_f32 v3, v66, v68, 1.0 op_sel:[0,0,1,1]
	v_cvt_scalef32_pk_f32_fp4 v[6:7], v0, 1.0 op_sel:[0,1,0]
	v_cvt_scalef32_pk_f32_fp4 v[8:9], v0, 1.0 op_sel:[1,1,0]
	v_mul_f32_e32 v70, 4.0, v69
	v_mul_f32_e32 v71, 4.0, v13
	v_fma_f32 v72, v15, s87, -v4
	v_fma_f32 v23, v23, s87, -v5
	v_cvt_scalef32_pk_f32_fp4 v[4:5], v1, 1.0 op_sel:[1,0,0]
	ds_write_b128 v10, v[0:3]
	v_mov_b32_e32 v0, v16
	v_mul_f32_e32 v73, 4.0, v72
	v_mul_f32_e32 v74, 4.0, v23
	v_fma_f32 v27, v27, s87, -v6
	v_fma_f32 v24, v24, s87, -v7
	v_fma_f32 v30, v30, s87, -v8
	v_fma_f32 v25, v25, s87, -v9
	v_cvt_scalef32_pk_f32_fp4 v[6:7], v1, 1.0 op_sel:[0,1,0]
	v_cvt_scalef32_pk_f32_fp4 v[8:9], v1, 1.0 op_sel:[1,1,0]
	v_mul_f32_e32 v22, 4.0, v11
	v_mul_f32_e32 v28, 4.0, v18
	v_fma_f32 v26, v26, s87, -v4
	v_fma_f32 v19, v19, s87, -v5
	v_cvt_scalef32_pk_fp4_f32 v0, v70, v71, 1.0
	v_mov_b32_e32 v1, v16
	v_mul_f32_e32 v75, 4.0, v27
	v_mul_f32_e32 v76, 4.0, v24
	v_mul_f32_e32 v29, 4.0, v26
	v_mul_f32_e32 v32, 4.0, v19
	v_fma_f32 v31, v31, s87, -v6
	v_fma_f32 v20, v20, s87, -v7
	v_cvt_scalef32_pk_fp4_f32 v0, v73, v74, 1.0 op_sel:[0,0,1,0]
	v_cvt_scalef32_pk_fp4_f32 v1, v22, v28, 1.0
	v_mul_f32_e32 v77, 4.0, v30
	v_mul_f32_e32 v78, 4.0, v25
	v_mul_f32_e32 v33, 4.0, v31
	v_mul_f32_e32 v35, 4.0, v20
	v_fma_f32 v34, v34, s87, -v8
	v_fma_f32 v21, v21, s87, -v9
	v_cvt_scalef32_pk_fp4_f32 v0, v75, v76, 1.0 op_sel:[0,0,0,1]
	v_cvt_scalef32_pk_fp4_f32 v1, v29, v32, 1.0 op_sel:[0,0,1,0]
	v_mul_f32_e32 v36, 4.0, v34
	v_mul_f32_e32 v79, 4.0, v21
	v_cvt_scalef32_pk_f32_fp4 v[4:5], v2, 1.0
	v_cvt_scalef32_pk_f32_fp4 v[6:7], v2, 1.0 op_sel:[1,0,0]
	v_cvt_scalef32_pk_f32_fp4 v[8:9], v2, 1.0 op_sel:[0,1,0]
	v_cvt_scalef32_pk_f32_fp4 v[14:15], v2, 1.0 op_sel:[1,1,0]
	v_cvt_scalef32_pk_fp4_f32 v0, v77, v78, 1.0 op_sel:[0,0,1,1]
	v_cvt_scalef32_pk_fp4_f32 v1, v33, v35, 1.0 op_sel:[0,0,0,1]
	v_fma_f32 v37, v37, s87, -v4
	v_fma_f32 v39, v39, s87, -v5
	v_fma_f32 v41, v41, s87, -v6
	v_fma_f32 v43, v43, s87, -v7
	v_fma_f32 v45, v45, s87, -v8
	v_fma_f32 v47, v47, s87, -v9
	v_fma_f32 v49, v49, s87, -v14
	v_fma_f32 v51, v51, s87, -v15
	v_cvt_scalef32_pk_f32_fp4 v[4:5], v3, 1.0
	v_cvt_scalef32_pk_f32_fp4 v[6:7], v3, 1.0 op_sel:[1,0,0]
	v_cvt_scalef32_pk_f32_fp4 v[8:9], v3, 1.0 op_sel:[0,1,0]
	v_cvt_scalef32_pk_f32_fp4 v[14:15], v3, 1.0 op_sel:[1,1,0]
	v_cvt_scalef32_pk_f32_fp4 v[2:3], v0, 1.0
	v_cvt_scalef32_pk_fp4_f32 v1, v36, v79, 1.0 op_sel:[0,0,1,1]
	v_fma_f32 v53, v53, s87, -v4
	v_fma_f32 v55, v55, s87, -v5
	v_fma_f32 v69, v69, 4.0, -v2
	v_fma_f32 v13, v13, 4.0, -v3
	v_cvt_scalef32_pk_f32_fp4 v[2:3], v1, 1.0
	v_mul_f32_e32 v38, 4.0, v37
	v_mul_f32_e32 v40, 4.0, v39
	v_mul_f32_e32 v54, 4.0, v53
	v_mul_f32_e32 v56, 4.0, v55
	v_fma_f32 v57, v57, s87, -v6
	v_fma_f32 v59, v59, s87, -v7
	v_fma_f32 v11, v11, 4.0, -v2
	v_fma_f32 v18, v18, 4.0, -v3
	v_mov_b32_e32 v2, v16
	v_mov_b32_e32 v3, v16
	v_mul_f32_e32 v42, 4.0, v41
	v_mul_f32_e32 v44, 4.0, v43
	v_mul_f32_e32 v58, 4.0, v57
	v_mul_f32_e32 v60, 4.0, v59
	v_fma_f32 v61, v61, s87, -v8
	v_fma_f32 v63, v63, s87, -v9
	v_cvt_scalef32_pk_fp4_f32 v2, v38, v40, 1.0
	v_cvt_scalef32_pk_fp4_f32 v3, v54, v56, 1.0
	v_mul_f32_e32 v46, 4.0, v45
	v_mul_f32_e32 v48, 4.0, v47
	v_mul_f32_e32 v62, 4.0, v61
	v_mul_f32_e32 v64, 4.0, v63
	v_fma_f32 v65, v65, s87, -v14
	v_fma_f32 v67, v67, s87, -v15
	v_cvt_scalef32_pk_fp4_f32 v2, v42, v44, 1.0 op_sel:[0,0,1,0]
	v_cvt_scalef32_pk_fp4_f32 v3, v58, v60, 1.0 op_sel:[0,0,1,0]
	v_mul_f32_e32 v50, 4.0, v49
	v_mul_f32_e32 v52, 4.0, v51
	v_mul_f32_e32 v66, 4.0, v65
	v_mul_f32_e32 v68, 4.0, v67
	v_cvt_scalef32_pk_fp4_f32 v2, v46, v48, 1.0 op_sel:[0,0,0,1]
	v_cvt_scalef32_pk_fp4_f32 v3, v62, v64, 1.0 op_sel:[0,0,0,1]
	v_cvt_scalef32_pk_f32_fp4 v[4:5], v0, 1.0 op_sel:[1,0,0]
	v_cvt_scalef32_pk_fp4_f32 v2, v50, v52, 1.0 op_sel:[0,0,1,1]
	v_cvt_scalef32_pk_fp4_f32 v3, v66, v68, 1.0 op_sel:[0,0,1,1]
	v_cvt_scalef32_pk_f32_fp4 v[6:7], v0, 1.0 op_sel:[0,1,0]
	v_cvt_scalef32_pk_f32_fp4 v[8:9], v0, 1.0 op_sel:[1,1,0]
	v_mul_f32_e32 v70, 4.0, v69
	v_mul_f32_e32 v71, 4.0, v13
	v_fma_f32 v72, v72, 4.0, -v4
	v_fma_f32 v23, v23, 4.0, -v5
	ds_write_b128 v10, v[0:3] offset:1024
	v_mov_b32_e32 v0, v16
	v_mul_f32_e32 v73, 4.0, v72
	v_mul_f32_e32 v74, 4.0, v23
	v_fma_f32 v27, v27, 4.0, -v6
	v_fma_f32 v24, v24, 4.0, -v7
	v_cvt_scalef32_pk_fp4_f32 v0, v70, v71, 1.0
	v_mul_f32_e32 v75, 4.0, v27
	v_mul_f32_e32 v76, 4.0, v24
	v_fma_f32 v30, v30, 4.0, -v8
	v_fma_f32 v25, v25, 4.0, -v9
	v_cvt_scalef32_pk_fp4_f32 v0, v73, v74, 1.0 op_sel:[0,0,1,0]
	v_mul_f32_e32 v77, 4.0, v30
	v_mul_f32_e32 v78, 4.0, v25
	v_cvt_scalef32_pk_f32_fp4 v[4:5], v1, 1.0 op_sel:[1,0,0]
	v_cvt_scalef32_pk_f32_fp4 v[6:7], v1, 1.0 op_sel:[0,1,0]
	v_cvt_scalef32_pk_f32_fp4 v[8:9], v1, 1.0 op_sel:[1,1,0]
	v_cvt_scalef32_pk_fp4_f32 v0, v75, v76, 1.0 op_sel:[0,0,0,1]
	v_fma_f32 v26, v26, 4.0, -v4
	v_fma_f32 v19, v19, 4.0, -v5
	v_fma_f32 v31, v31, 4.0, -v6
	v_fma_f32 v20, v20, 4.0, -v7
	v_fma_f32 v34, v34, 4.0, -v8
	v_fma_f32 v21, v21, 4.0, -v9
	v_cvt_scalef32_pk_f32_fp4 v[4:5], v2, 1.0
	v_cvt_scalef32_pk_f32_fp4 v[6:7], v2, 1.0 op_sel:[1,0,0]
	v_cvt_scalef32_pk_f32_fp4 v[8:9], v2, 1.0 op_sel:[0,1,0]
	v_cvt_scalef32_pk_f32_fp4 v[14:15], v2, 1.0 op_sel:[1,1,0]
	v_cvt_scalef32_pk_fp4_f32 v0, v77, v78, 1.0 op_sel:[0,0,1,1]
	v_fma_f32 v37, v37, 4.0, -v4
	v_fma_f32 v39, v39, 4.0, -v5
	v_fma_f32 v41, v41, 4.0, -v6
	v_fma_f32 v43, v43, 4.0, -v7
	v_fma_f32 v45, v45, 4.0, -v8
	v_fma_f32 v47, v47, 4.0, -v9
	v_fma_f32 v49, v49, 4.0, -v14
	v_fma_f32 v51, v51, 4.0, -v15
	v_cvt_scalef32_pk_f32_fp4 v[4:5], v3, 1.0
	v_cvt_scalef32_pk_f32_fp4 v[6:7], v3, 1.0 op_sel:[1,0,0]
	v_cvt_scalef32_pk_f32_fp4 v[8:9], v3, 1.0 op_sel:[0,1,0]
	v_cvt_scalef32_pk_f32_fp4 v[14:15], v3, 1.0 op_sel:[1,1,0]
	v_cvt_scalef32_pk_f32_fp4 v[2:3], v0, 1.0
	v_fma_f32 v1, v69, 4.0, -v2
	v_fma_f32 v53, v53, 4.0, -v4
	v_fma_f32 v55, v55, 4.0, -v5
	v_cvt_scalef32_pk_f32_fp4 v[4:5], v0, 1.0 op_sel:[1,0,0]
	v_mul_f32_e32 v69, 4.0, v1
	v_fma_f32 v1, v13, 4.0, -v3
	v_mul_f32_e32 v13, 4.0, v1
	v_fma_f32 v1, v72, 4.0, -v4
	v_fma_f32 v57, v57, 4.0, -v6
	v_fma_f32 v59, v59, 4.0, -v7
	v_cvt_scalef32_pk_f32_fp4 v[6:7], v0, 1.0 op_sel:[0,1,0]
	v_mul_f32_e32 v70, 4.0, v1
	v_fma_f32 v1, v23, 4.0, -v5
	v_mul_f32_e32 v23, 4.0, v1
	v_fma_f32 v1, v27, 4.0, -v6
	v_fma_f32 v61, v61, 4.0, -v8
	v_fma_f32 v63, v63, 4.0, -v9
	v_cvt_scalef32_pk_f32_fp4 v[8:9], v0, 1.0 op_sel:[1,1,0]
	v_mul_f32_e32 v27, 4.0, v1
	v_fma_f32 v1, v24, 4.0, -v7
	v_mul_f32_e32 v24, 4.0, v1
	v_fma_f32 v1, v30, 4.0, -v8
	v_mul_f32_e32 v30, 4.0, v1
	v_fma_f32 v1, v25, 4.0, -v9
	v_mul_f32_e32 v22, 4.0, v11
	v_mul_f32_e32 v28, 4.0, v18
	v_mul_f32_e32 v25, 4.0, v1
	v_mov_b32_e32 v1, v16
	v_mul_f32_e32 v29, 4.0, v26
	v_mul_f32_e32 v32, 4.0, v19
	v_cvt_scalef32_pk_fp4_f32 v1, v22, v28, 1.0
	v_mul_f32_e32 v33, 4.0, v31
	v_mul_f32_e32 v35, 4.0, v20
	v_cvt_scalef32_pk_fp4_f32 v1, v29, v32, 1.0 op_sel:[0,0,1,0]
	v_mul_f32_e32 v36, 4.0, v34
	v_mul_f32_e32 v79, 4.0, v21
	v_cvt_scalef32_pk_fp4_f32 v1, v33, v35, 1.0 op_sel:[0,0,0,1]
	v_mul_f32_e32 v38, 4.0, v37
	v_cvt_scalef32_pk_fp4_f32 v1, v36, v79, 1.0 op_sel:[0,0,1,1]
	v_mul_f32_e32 v40, 4.0, v39
	v_cvt_scalef32_pk_f32_fp4 v[2:3], v1, 1.0
	v_fma_f32 v2, v11, 4.0, -v2
	v_cvt_scalef32_pk_f32_fp4 v[4:5], v1, 1.0 op_sel:[1,0,0]
	v_mul_f32_e32 v11, 4.0, v2
	v_fma_f32 v2, v18, 4.0, -v3
	v_mul_f32_e32 v18, 4.0, v2
	v_fma_f32 v2, v26, 4.0, -v4
	v_cvt_scalef32_pk_f32_fp4 v[6:7], v1, 1.0 op_sel:[0,1,0]
	v_mul_f32_e32 v22, 4.0, v2
	v_fma_f32 v2, v19, 4.0, -v5
	v_mul_f32_e32 v19, 4.0, v2
	v_fma_f32 v2, v31, 4.0, -v6
	v_cvt_scalef32_pk_f32_fp4 v[8:9], v1, 1.0 op_sel:[1,1,0]
	v_mul_f32_e32 v26, 4.0, v2
	v_fma_f32 v2, v20, 4.0, -v7
	v_mul_f32_e32 v20, 4.0, v2
	v_fma_f32 v2, v34, 4.0, -v8
	v_mul_f32_e32 v28, 4.0, v2
	v_fma_f32 v2, v21, 4.0, -v9
	v_mul_f32_e32 v21, 4.0, v2
	v_mov_b32_e32 v2, v16
	v_mul_f32_e32 v42, 4.0, v41
	v_mul_f32_e32 v44, 4.0, v43
	v_cvt_scalef32_pk_fp4_f32 v2, v38, v40, 1.0
	v_mul_f32_e32 v46, 4.0, v45
	v_mul_f32_e32 v48, 4.0, v47
	v_cvt_scalef32_pk_fp4_f32 v2, v42, v44, 1.0 op_sel:[0,0,1,0]
	v_mul_f32_e32 v50, 4.0, v49
	v_mul_f32_e32 v52, 4.0, v51
	v_cvt_scalef32_pk_fp4_f32 v2, v46, v48, 1.0 op_sel:[0,0,0,1]
	v_fma_f32 v65, v65, 4.0, -v14
	v_cvt_scalef32_pk_fp4_f32 v2, v50, v52, 1.0 op_sel:[0,0,1,1]
	v_fma_f32 v67, v67, 4.0, -v15
	v_cvt_scalef32_pk_f32_fp4 v[4:5], v2, 1.0
	v_fma_f32 v3, v37, 4.0, -v4
	v_cvt_scalef32_pk_f32_fp4 v[6:7], v2, 1.0 op_sel:[1,0,0]
	v_mul_f32_e32 v29, 4.0, v3
	v_fma_f32 v3, v39, 4.0, -v5
	v_mul_f32_e32 v31, 4.0, v3
	v_fma_f32 v3, v41, 4.0, -v6
	v_cvt_scalef32_pk_f32_fp4 v[8:9], v2, 1.0 op_sel:[0,1,0]
	v_mul_f32_e32 v32, 4.0, v3
	v_fma_f32 v3, v43, 4.0, -v7
	v_mul_f32_e32 v33, 4.0, v3
	v_fma_f32 v3, v45, 4.0, -v8
	v_cvt_scalef32_pk_f32_fp4 v[14:15], v2, 1.0 op_sel:[1,1,0]
	v_mul_f32_e32 v34, 4.0, v3
	v_fma_f32 v3, v47, 4.0, -v9
	v_mul_f32_e32 v35, 4.0, v3
	v_fma_f32 v3, v49, 4.0, -v14
	v_mul_f32_e32 v36, 4.0, v3
	v_fma_f32 v3, v51, 4.0, -v15
	v_mul_f32_e32 v54, 4.0, v53
	v_mul_f32_e32 v56, 4.0, v55
	v_mul_f32_e32 v37, 4.0, v3
	v_mov_b32_e32 v3, v16
	v_mul_f32_e32 v58, 4.0, v57
	v_mul_f32_e32 v60, 4.0, v59
	v_cvt_scalef32_pk_fp4_f32 v3, v54, v56, 1.0
	v_mul_f32_e32 v62, 4.0, v61
	v_mul_f32_e32 v64, 4.0, v63
	v_cvt_scalef32_pk_fp4_f32 v3, v58, v60, 1.0 op_sel:[0,0,1,0]
	v_mul_f32_e32 v66, 4.0, v65
	v_mul_f32_e32 v68, 4.0, v67
	v_cvt_scalef32_pk_fp4_f32 v3, v62, v64, 1.0 op_sel:[0,0,0,1]
	s_nop 0
	v_cvt_scalef32_pk_fp4_f32 v3, v66, v68, 1.0 op_sel:[0,0,1,1]
	ds_write_b128 v10, v[0:3] offset:2048
	v_cvt_scalef32_pk_f32_fp4 v[4:5], v3, 1.0
	v_cvt_scalef32_pk_f32_fp4 v[6:7], v3, 1.0 op_sel:[1,0,0]
	v_fma_f32 v4, v53, 4.0, -v4
	v_fma_f32 v5, v55, 4.0, -v5
	v_cvt_scalef32_pk_f32_fp4 v[8:9], v3, 1.0 op_sel:[0,1,0]
	v_cvt_scalef32_pk_f32_fp4 v[14:15], v3, 1.0 op_sel:[1,1,0]
	v_mul_f32_e32 v4, 4.0, v4
	v_mul_f32_e32 v5, 4.0, v5
	v_fma_f32 v6, v57, 4.0, -v6
	v_fma_f32 v7, v59, 4.0, -v7
	v_mov_b32_e32 v0, v16
	v_mov_b32_e32 v1, v16
	v_mov_b32_e32 v2, v16
	v_mov_b32_e32 v3, v16
	v_mul_f32_e32 v6, 4.0, v6
	v_mul_f32_e32 v7, 4.0, v7
	v_fma_f32 v8, v61, 4.0, -v8
	v_fma_f32 v9, v63, 4.0, -v9
	v_cvt_scalef32_pk_fp4_f32 v0, v69, v13, 1.0
	v_cvt_scalef32_pk_fp4_f32 v1, v11, v18, 1.0
	v_cvt_scalef32_pk_fp4_f32 v2, v29, v31, 1.0
	v_cvt_scalef32_pk_fp4_f32 v3, v4, v5, 1.0
	v_mul_f32_e32 v8, 4.0, v8
	v_mul_f32_e32 v9, 4.0, v9
	v_fma_f32 v14, v65, 4.0, -v14
	v_fma_f32 v15, v67, 4.0, -v15
	v_cvt_scalef32_pk_fp4_f32 v0, v70, v23, 1.0 op_sel:[0,0,1,0]
	v_cvt_scalef32_pk_fp4_f32 v1, v22, v19, 1.0 op_sel:[0,0,1,0]
	v_cvt_scalef32_pk_fp4_f32 v2, v32, v33, 1.0 op_sel:[0,0,1,0]
	v_cvt_scalef32_pk_fp4_f32 v3, v6, v7, 1.0 op_sel:[0,0,1,0]
	v_mul_f32_e32 v14, 4.0, v14
	v_mul_f32_e32 v15, 4.0, v15
	v_cvt_scalef32_pk_fp4_f32 v0, v27, v24, 1.0 op_sel:[0,0,0,1]
	v_cvt_scalef32_pk_fp4_f32 v1, v26, v20, 1.0 op_sel:[0,0,0,1]
	v_cvt_scalef32_pk_fp4_f32 v2, v34, v35, 1.0 op_sel:[0,0,0,1]
	v_cvt_scalef32_pk_fp4_f32 v3, v8, v9, 1.0 op_sel:[0,0,0,1]
	v_cvt_scalef32_pk_fp4_f32 v0, v30, v25, 1.0 op_sel:[0,0,1,1]
	v_cvt_scalef32_pk_fp4_f32 v1, v28, v21, 1.0 op_sel:[0,0,1,1]
	v_cvt_scalef32_pk_fp4_f32 v2, v36, v37, 1.0 op_sel:[0,0,1,1]
	v_cvt_scalef32_pk_fp4_f32 v3, v14, v15, 1.0 op_sel:[0,0,1,1]
	ds_write_b128 v10, v[0:3] offset:3072
	v_lshl_add_u32 v0, v158, 2, v12
	v_add_u32_e32 v13, 0x8000, v0
	ds_read2_b32 v[2:3], v13 offset1:16
	ds_read2_b32 v[6:7], v13 offset0:32 offset1:48
	ds_read2_b32 v[10:11], v13 offset0:64 offset1:80
	s_waitcnt lgkmcnt(2)
	v_ashrrev_i32_e32 v5, 31, v3
	v_mov_b32_e32 v4, v3
	s_waitcnt lgkmcnt(1)
	v_ashrrev_i32_e32 v9, 31, v7
	v_mov_b32_e32 v8, v7
	s_waitcnt lgkmcnt(0)
	v_ashrrev_i32_e32 v15, 31, v11
	v_mov_b32_e32 v14, v11
	v_ashrrev_i32_e32 v1, 31, v2
	v_mov_b32_e32 v0, v2
	v_lshlrev_b64 v[2:3], 10, v[4:5]
	v_ashrrev_i32_e32 v5, 31, v6
	v_mov_b32_e32 v4, v6
	v_lshlrev_b64 v[6:7], 10, v[8:9]
	v_ashrrev_i32_e32 v9, 31, v10
	v_mov_b32_e32 v8, v10
	v_lshlrev_b64 v[10:11], 10, v[14:15]
	ds_read2_b32 v[14:15], v13 offset0:96 offset1:112
	v_lshlrev_b64 v[0:1], 10, v[0:1]
	v_lshl_add_u64 v[0:1], s[12:13], 0, v[0:1]
	v_lshlrev_b64 v[4:5], 10, v[4:5]
	v_lshlrev_b64 v[8:9], 10, v[8:9]
	s_waitcnt lgkmcnt(0)
	v_ashrrev_i32_e32 v19, 31, v14
	v_mov_b32_e32 v18, v14
	v_ashrrev_i32_e32 v21, 31, v15
	v_mov_b32_e32 v20, v15
	v_lshlrev_b64 v[18:19], 10, v[18:19]
	v_lshlrev_b64 v[14:15], 10, v[20:21]
	v_lshl_add_u64 v[0:1], v[0:1], 0, v[152:153]
	v_lshl_add_u64 v[2:3], s[12:13], 0, v[2:3]
	v_lshl_add_u64 v[4:5], s[12:13], 0, v[4:5]
	v_lshl_add_u64 v[6:7], s[12:13], 0, v[6:7]
	v_lshl_add_u64 v[8:9], s[12:13], 0, v[8:9]
	v_lshl_add_u64 v[10:11], s[12:13], 0, v[10:11]
	v_lshl_add_u64 v[18:19], s[12:13], 0, v[18:19]
	v_lshl_add_u64 v[14:15], s[12:13], 0, v[14:15]
	v_lshl_add_u64 v[2:3], v[2:3], 0, v[152:153]
	v_lshl_add_u64 v[4:5], v[4:5], 0, v[152:153]
	v_lshl_add_u64 v[6:7], v[6:7], 0, v[152:153]
	v_lshl_add_u64 v[8:9], v[8:9], 0, v[152:153]
	v_lshl_add_u64 v[10:11], v[10:11], 0, v[152:153]
	v_lshl_add_u64 v[18:19], v[18:19], 0, v[152:153]
	v_lshl_add_u64 v[20:21], v[14:15], 0, v[152:153]
	s_lshl_b32 s99, s61, 12
	v_lshl_add_u32 v242, v214, 6, s99
	v_mov_b32_e32 v243, 0
	v_lshl_add_u64 v[244:245], v[178:179], 0, v[242:243]
	s_lshl_b32 s98, s90, 12
	s_add_i32 s98, s98, 0x1b000
	s_mov_b32 m0, s98
	s_nop 0
	global_load_lds_dwordx4 v[244:245], off
	s_add_i32 m0, s98, 1008
	s_nop 0
	global_load_lds_dwordx4 v[244:245], off offset:16
	s_add_i32 m0, s98, 2016
	s_nop 0
	global_load_lds_dwordx4 v[244:245], off offset:32
	s_add_i32 m0, s98, 3024
	s_nop 0
	global_load_lds_dwordx4 v[244:245], off offset:48
	s_mov_b32 s100, 1
	global_load_dwordx4 v[22:25], v[0:1], off
	global_load_dwordx4 v[26:29], v[0:1], off offset:64
	global_load_dwordx4 v[30:33], v[2:3], off
	global_load_dwordx4 v[34:37], v[2:3], off offset:64
	global_load_dwordx4 v[38:41], v[4:5], off
	global_load_dwordx4 v[42:45], v[4:5], off offset:64
	global_load_dwordx4 v[46:49], v[6:7], off
	global_load_dwordx4 v[56:59], v[6:7], off offset:64
	global_load_dwordx4 v[60:63], v[8:9], off
	global_load_dwordx4 v[64:67], v[8:9], off offset:64
	global_load_dwordx4 v[72:75], v[10:11], off
	global_load_dwordx4 v[76:79], v[10:11], off offset:64
	global_load_dwordx4 v[80:83], v[18:19], off
	global_load_dwordx4 v[84:87], v[18:19], off offset:64
	global_load_dwordx4 v[88:91], v[20:21], off
	global_load_dwordx4 v[92:95], v[20:21], off offset:64
	v_lshlrev_b32_e32 v14, 4, v158
	v_mov_b32_e32 v15, v16
	v_and_b32_e32 v153, 0xffffff80, v224
	v_lshlrev_b32_e32 v13, 10, v154
	v_lshl_add_u64 v[14:15], s[10:11], 0, v[14:15]
	v_add_u32_e32 v225, v12, v153
	v_add3_u32 v70, v216, v13, v152
	v_lshl_add_u64 v[182:183], v[14:15], 0, s[0:1]
	ds_read_b128 v[52:55], v225 offset:32768
	ds_read_b128 v[12:15], v225 offset:32784
	global_load_dwordx4 v[96:99], v[0:1], off offset:128
	global_load_dwordx4 v[100:103], v[0:1], off offset:192
	global_load_dwordx4 v[104:107], v[2:3], off offset:128
	global_load_dwordx4 v[108:111], v[2:3], off offset:192
	global_load_dwordx4 v[112:115], v[4:5], off offset:128
	global_load_dwordx4 v[116:119], v[4:5], off offset:192
	global_load_dwordx4 v[120:123], v[6:7], off offset:128
	global_load_dwordx4 v[124:127], v[6:7], off offset:192
	ds_read_b128 v[128:131], v70 offset:64
	ds_read_b128 v[132:135], v70
	s_waitcnt vmcnt(23) lgkmcnt(0)
	v_mfma_scale_f32_16x16x128_f8f6f4 v[22:25], v[22:25], v[132:135], 0, v187, v187 op_sel_hi:[0,0,0] cbsz:4 blgp:4
	s_waitcnt vmcnt(22)
	v_mfma_scale_f32_16x16x128_f8f6f4 v[22:25], v[26:29], v[128:131], v[22:25], v187, v187 op_sel_hi:[0,0,0] cbsz:4 blgp:4
	s_waitcnt vmcnt(21)
	v_mfma_scale_f32_16x16x128_f8f6f4 v[26:29], v[30:33], v[132:135], 0, v187, v187 op_sel_hi:[0,0,0] cbsz:4 blgp:4
	s_waitcnt vmcnt(20)
	v_mfma_scale_f32_16x16x128_f8f6f4 v[26:29], v[34:37], v[128:131], v[26:29], v187, v187 op_sel_hi:[0,0,0] cbsz:4 blgp:4
	s_waitcnt vmcnt(19)
	v_mfma_scale_f32_16x16x128_f8f6f4 v[30:33], v[38:41], v[132:135], 0, v187, v187 op_sel_hi:[0,0,0] cbsz:4 blgp:4
	s_waitcnt vmcnt(17)
	v_mfma_scale_f32_16x16x128_f8f6f4 v[34:37], v[46:49], v[132:135], 0, v187, v187 op_sel_hi:[0,0,0] cbsz:4 blgp:4
	v_mfma_scale_f32_16x16x128_f8f6f4 v[30:33], v[42:45], v[128:131], v[30:33], v187, v187 op_sel_hi:[0,0,0] cbsz:4 blgp:4
	s_waitcnt vmcnt(16)
	v_mfma_scale_f32_16x16x128_f8f6f4 v[34:37], v[56:59], v[128:131], v[34:37], v187, v187 op_sel_hi:[0,0,0] cbsz:4 blgp:4
	global_load_dwordx4 v[38:41], v[8:9], off offset:128
	global_load_dwordx4 v[42:45], v[8:9], off offset:192
	global_load_dwordx4 v[46:49], v[10:11], off offset:128
	global_load_dwordx4 v[56:59], v[10:11], off offset:192
	global_load_dwordx4 v[136:139], v[18:19], off offset:128
	global_load_dwordx4 v[140:143], v[18:19], off offset:192
	global_load_dwordx4 v[144:147], v[20:21], off offset:128
	global_load_dwordx4 v[160:163], v[20:21], off offset:192
	s_waitcnt vmcnt(23)
	v_mfma_scale_f32_16x16x128_f8f6f4 v[60:63], v[60:63], v[132:135], 0, v187, v187 op_sel_hi:[0,0,0] cbsz:4 blgp:4
	s_waitcnt vmcnt(22)
	v_mfma_scale_f32_16x16x128_f8f6f4 v[60:63], v[64:67], v[128:131], v[60:63], v187, v187 op_sel_hi:[0,0,0] cbsz:4 blgp:4
	s_waitcnt vmcnt(21)
	v_mfma_scale_f32_16x16x128_f8f6f4 v[64:67], v[72:75], v[132:135], 0, v187, v187 op_sel_hi:[0,0,0] cbsz:4 blgp:4
	s_waitcnt vmcnt(20)
	v_mfma_scale_f32_16x16x128_f8f6f4 v[64:67], v[76:79], v[128:131], v[64:67], v187, v187 op_sel_hi:[0,0,0] cbsz:4 blgp:4
	s_waitcnt vmcnt(19)
	v_mfma_scale_f32_16x16x128_f8f6f4 v[72:75], v[80:83], v[132:135], 0, v187, v187 op_sel_hi:[0,0,0] cbsz:4 blgp:4
	s_waitcnt vmcnt(17)
	v_mfma_scale_f32_16x16x128_f8f6f4 v[76:79], v[88:91], v[132:135], 0, v187, v187 op_sel_hi:[0,0,0] cbsz:4 blgp:4
	v_mfma_scale_f32_16x16x128_f8f6f4 v[72:75], v[84:87], v[128:131], v[72:75], v187, v187 op_sel_hi:[0,0,0] cbsz:4 blgp:4
	s_waitcnt vmcnt(16)
	v_mfma_scale_f32_16x16x128_f8f6f4 v[76:79], v[92:95], v[128:131], v[76:79], v187, v187 op_sel_hi:[0,0,0] cbsz:4 blgp:4
	global_load_dwordx4 v[80:83], v[0:1], off offset:256
	global_load_dwordx4 v[84:87], v[0:1], off offset:320
	global_load_dwordx4 v[88:91], v[2:3], off offset:256
	global_load_dwordx4 v[92:95], v[2:3], off offset:320
	global_load_dwordx4 v[128:131], v[4:5], off offset:256
	global_load_dwordx4 v[132:135], v[4:5], off offset:320
	global_load_dwordx4 v[164:167], v[6:7], off offset:256
	global_load_dwordx4 v[168:171], v[6:7], off offset:320
	ds_read_b128 v[172:175], v70 offset:192
	ds_read_b128 v[196:199], v70 offset:128
	s_waitcnt vmcnt(23) lgkmcnt(0)
	v_mfma_scale_f32_16x16x128_f8f6f4 v[22:25], v[96:99], v[196:199], v[22:25], v187, v187 op_sel_hi:[0,0,0] cbsz:4 blgp:4
	s_waitcnt vmcnt(21)
	v_mfma_scale_f32_16x16x128_f8f6f4 v[26:29], v[104:107], v[196:199], v[26:29], v187, v187 op_sel_hi:[0,0,0] cbsz:4 blgp:4
	s_waitcnt vmcnt(19)
	v_mfma_scale_f32_16x16x128_f8f6f4 v[30:33], v[112:115], v[196:199], v[30:33], v187, v187 op_sel_hi:[0,0,0] cbsz:4 blgp:4
	s_waitcnt vmcnt(17)
	v_mfma_scale_f32_16x16x128_f8f6f4 v[34:37], v[120:123], v[196:199], v[34:37], v187, v187 op_sel_hi:[0,0,0] cbsz:4 blgp:4
	v_mfma_scale_f32_16x16x128_f8f6f4 v[22:25], v[100:103], v[172:175], v[22:25], v187, v187 op_sel_hi:[0,0,0] cbsz:4 blgp:4
	v_mfma_scale_f32_16x16x128_f8f6f4 v[26:29], v[108:111], v[172:175], v[26:29], v187, v187 op_sel_hi:[0,0,0] cbsz:4 blgp:4
	v_mfma_scale_f32_16x16x128_f8f6f4 v[30:33], v[116:119], v[172:175], v[30:33], v187, v187 op_sel_hi:[0,0,0] cbsz:4 blgp:4
	s_waitcnt vmcnt(16)
	v_mfma_scale_f32_16x16x128_f8f6f4 v[34:37], v[124:127], v[172:175], v[34:37], v187, v187 op_sel_hi:[0,0,0] cbsz:4 blgp:4
	global_load_dwordx4 v[96:99], v[8:9], off offset:256
	global_load_dwordx4 v[100:103], v[8:9], off offset:320
	global_load_dwordx4 v[104:107], v[10:11], off offset:256
	global_load_dwordx4 v[108:111], v[10:11], off offset:320
	global_load_dwordx4 v[112:115], v[18:19], off offset:256
	global_load_dwordx4 v[116:119], v[18:19], off offset:320
	global_load_dwordx4 v[120:123], v[20:21], off offset:256
	global_load_dwordx4 v[124:127], v[20:21], off offset:320
	s_waitcnt vmcnt(23)
	v_mfma_scale_f32_16x16x128_f8f6f4 v[38:41], v[38:41], v[196:199], v[60:63], v187, v187 op_sel_hi:[0,0,0] cbsz:4 blgp:4
	s_waitcnt vmcnt(22)
	v_mfma_scale_f32_16x16x128_f8f6f4 v[38:41], v[42:45], v[172:175], v[38:41], v187, v187 op_sel_hi:[0,0,0] cbsz:4 blgp:4
	s_waitcnt vmcnt(21)
	v_mfma_scale_f32_16x16x128_f8f6f4 v[42:45], v[46:49], v[196:199], v[64:67], v187, v187 op_sel_hi:[0,0,0] cbsz:4 blgp:4
	s_waitcnt vmcnt(20)
	v_mfma_scale_f32_16x16x128_f8f6f4 v[42:45], v[56:59], v[172:175], v[42:45], v187, v187 op_sel_hi:[0,0,0] cbsz:4 blgp:4
	s_waitcnt vmcnt(19)
	v_mfma_scale_f32_16x16x128_f8f6f4 v[46:49], v[136:139], v[196:199], v[72:75], v187, v187 op_sel_hi:[0,0,0] cbsz:4 blgp:4
	s_waitcnt vmcnt(17)
	v_mfma_scale_f32_16x16x128_f8f6f4 v[56:59], v[144:147], v[196:199], v[76:79], v187, v187 op_sel_hi:[0,0,0] cbsz:4 blgp:4
	v_mfma_scale_f32_16x16x128_f8f6f4 v[46:49], v[140:143], v[172:175], v[46:49], v187, v187 op_sel_hi:[0,0,0] cbsz:4 blgp:4
	s_waitcnt vmcnt(16)
	v_mfma_scale_f32_16x16x128_f8f6f4 v[56:59], v[160:163], v[172:175], v[56:59], v187, v187 op_sel_hi:[0,0,0] cbsz:4 blgp:4
	global_load_dwordx4 v[60:63], v[0:1], off offset:384
	global_load_dwordx4 v[64:67], v[0:1], off offset:448
	global_load_dwordx4 v[72:75], v[2:3], off offset:384
	global_load_dwordx4 v[76:79], v[2:3], off offset:448
	global_load_dwordx4 v[136:139], v[4:5], off offset:384
	global_load_dwordx4 v[140:143], v[4:5], off offset:448
	global_load_dwordx4 v[144:147], v[6:7], off offset:384
	global_load_dwordx4 v[160:163], v[6:7], off offset:448
	ds_read_b128 v[172:175], v70 offset:320
	ds_read_b128 v[196:199], v70 offset:256
	s_waitcnt vmcnt(23) lgkmcnt(0)
	v_mfma_scale_f32_16x16x128_f8f6f4 v[22:25], v[80:83], v[196:199], v[22:25], v187, v187 op_sel_hi:[0,0,0] cbsz:4 blgp:4
	s_waitcnt vmcnt(21)
	v_mfma_scale_f32_16x16x128_f8f6f4 v[26:29], v[88:91], v[196:199], v[26:29], v187, v187 op_sel_hi:[0,0,0] cbsz:4 blgp:4
	s_waitcnt vmcnt(19)
	v_mfma_scale_f32_16x16x128_f8f6f4 v[30:33], v[128:131], v[196:199], v[30:33], v187, v187 op_sel_hi:[0,0,0] cbsz:4 blgp:4
	s_waitcnt vmcnt(17)
	v_mfma_scale_f32_16x16x128_f8f6f4 v[34:37], v[164:167], v[196:199], v[34:37], v187, v187 op_sel_hi:[0,0,0] cbsz:4 blgp:4
	v_mfma_scale_f32_16x16x128_f8f6f4 v[22:25], v[84:87], v[172:175], v[22:25], v187, v187 op_sel_hi:[0,0,0] cbsz:4 blgp:4
	v_mfma_scale_f32_16x16x128_f8f6f4 v[26:29], v[92:95], v[172:175], v[26:29], v187, v187 op_sel_hi:[0,0,0] cbsz:4 blgp:4
	v_mfma_scale_f32_16x16x128_f8f6f4 v[30:33], v[132:135], v[172:175], v[30:33], v187, v187 op_sel_hi:[0,0,0] cbsz:4 blgp:4
	s_waitcnt vmcnt(16)
	v_mfma_scale_f32_16x16x128_f8f6f4 v[34:37], v[168:171], v[172:175], v[34:37], v187, v187 op_sel_hi:[0,0,0] cbsz:4 blgp:4
	global_load_dwordx4 v[80:83], v[8:9], off offset:384
	global_load_dwordx4 v[84:87], v[8:9], off offset:448
	global_load_dwordx4 v[88:91], v[10:11], off offset:384
	global_load_dwordx4 v[92:95], v[10:11], off offset:448
	global_load_dwordx4 v[128:131], v[18:19], off offset:384
	global_load_dwordx4 v[132:135], v[18:19], off offset:448
	global_load_dwordx4 v[164:167], v[20:21], off offset:384
	global_load_dwordx4 v[168:171], v[20:21], off offset:448
	s_waitcnt vmcnt(23)
	v_mfma_scale_f32_16x16x128_f8f6f4 v[38:41], v[96:99], v[196:199], v[38:41], v187, v187 op_sel_hi:[0,0,0] cbsz:4 blgp:4
	s_waitcnt vmcnt(21)
	v_mfma_scale_f32_16x16x128_f8f6f4 v[42:45], v[104:107], v[196:199], v[42:45], v187, v187 op_sel_hi:[0,0,0] cbsz:4 blgp:4
	s_waitcnt vmcnt(19)
	v_mfma_scale_f32_16x16x128_f8f6f4 v[46:49], v[112:115], v[196:199], v[46:49], v187, v187 op_sel_hi:[0,0,0] cbsz:4 blgp:4
	s_waitcnt vmcnt(17)
	v_mfma_scale_f32_16x16x128_f8f6f4 v[56:59], v[120:123], v[196:199], v[56:59], v187, v187 op_sel_hi:[0,0,0] cbsz:4 blgp:4
	v_mfma_scale_f32_16x16x128_f8f6f4 v[38:41], v[100:103], v[172:175], v[38:41], v187, v187 op_sel_hi:[0,0,0] cbsz:4 blgp:4
	v_mfma_scale_f32_16x16x128_f8f6f4 v[42:45], v[108:111], v[172:175], v[42:45], v187, v187 op_sel_hi:[0,0,0] cbsz:4 blgp:4
	v_mfma_scale_f32_16x16x128_f8f6f4 v[46:49], v[116:119], v[172:175], v[46:49], v187, v187 op_sel_hi:[0,0,0] cbsz:4 blgp:4
	s_waitcnt vmcnt(16)
	v_mfma_scale_f32_16x16x128_f8f6f4 v[56:59], v[124:127], v[172:175], v[56:59], v187, v187 op_sel_hi:[0,0,0] cbsz:4 blgp:4
	global_load_dwordx4 v[96:99], v[0:1], off offset:512
	global_load_dwordx4 v[100:103], v[0:1], off offset:576
	global_load_dwordx4 v[104:107], v[2:3], off offset:512
	global_load_dwordx4 v[108:111], v[2:3], off offset:576
	global_load_dwordx4 v[112:115], v[4:5], off offset:512
	global_load_dwordx4 v[116:119], v[4:5], off offset:576
	global_load_dwordx4 v[120:123], v[6:7], off offset:512
	global_load_dwordx4 v[124:127], v[6:7], off offset:576
	ds_read_b128 v[172:175], v70 offset:448
	ds_read_b128 v[196:199], v70 offset:384
	s_waitcnt vmcnt(23) lgkmcnt(0)
	v_mfma_scale_f32_16x16x128_f8f6f4 v[22:25], v[60:63], v[196:199], v[22:25], v187, v187 op_sel_hi:[0,0,0] cbsz:4 blgp:4
	s_waitcnt vmcnt(21)
	v_mfma_scale_f32_16x16x128_f8f6f4 v[26:29], v[72:75], v[196:199], v[26:29], v187, v187 op_sel_hi:[0,0,0] cbsz:4 blgp:4
	s_waitcnt vmcnt(19)
	v_mfma_scale_f32_16x16x128_f8f6f4 v[30:33], v[136:139], v[196:199], v[30:33], v187, v187 op_sel_hi:[0,0,0] cbsz:4 blgp:4
	s_waitcnt vmcnt(17)
	v_mfma_scale_f32_16x16x128_f8f6f4 v[34:37], v[144:147], v[196:199], v[34:37], v187, v187 op_sel_hi:[0,0,0] cbsz:4 blgp:4
	v_mfma_scale_f32_16x16x128_f8f6f4 v[22:25], v[64:67], v[172:175], v[22:25], v187, v187 op_sel_hi:[0,0,0] cbsz:4 blgp:4
	v_mfma_scale_f32_16x16x128_f8f6f4 v[26:29], v[76:79], v[172:175], v[26:29], v187, v187 op_sel_hi:[0,0,0] cbsz:4 blgp:4
	v_mfma_scale_f32_16x16x128_f8f6f4 v[30:33], v[140:143], v[172:175], v[30:33], v187, v187 op_sel_hi:[0,0,0] cbsz:4 blgp:4
	s_waitcnt vmcnt(16)
	v_mfma_scale_f32_16x16x128_f8f6f4 v[34:37], v[160:163], v[172:175], v[34:37], v187, v187 op_sel_hi:[0,0,0] cbsz:4 blgp:4
	global_load_dwordx4 v[60:63], v[8:9], off offset:512
	global_load_dwordx4 v[64:67], v[8:9], off offset:576
	global_load_dwordx4 v[72:75], v[10:11], off offset:512
	global_load_dwordx4 v[76:79], v[10:11], off offset:576
	global_load_dwordx4 v[136:139], v[18:19], off offset:512
	global_load_dwordx4 v[140:143], v[18:19], off offset:576
	global_load_dwordx4 v[144:147], v[20:21], off offset:512
	global_load_dwordx4 v[160:163], v[20:21], off offset:576
	s_waitcnt vmcnt(23)
	v_mfma_scale_f32_16x16x128_f8f6f4 v[38:41], v[80:83], v[196:199], v[38:41], v187, v187 op_sel_hi:[0,0,0] cbsz:4 blgp:4
	s_waitcnt vmcnt(21)
	v_mfma_scale_f32_16x16x128_f8f6f4 v[42:45], v[88:91], v[196:199], v[42:45], v187, v187 op_sel_hi:[0,0,0] cbsz:4 blgp:4
	s_waitcnt vmcnt(19)
	v_mfma_scale_f32_16x16x128_f8f6f4 v[46:49], v[128:131], v[196:199], v[46:49], v187, v187 op_sel_hi:[0,0,0] cbsz:4 blgp:4
	s_waitcnt vmcnt(17)
	v_mfma_scale_f32_16x16x128_f8f6f4 v[56:59], v[164:167], v[196:199], v[56:59], v187, v187 op_sel_hi:[0,0,0] cbsz:4 blgp:4
	v_mfma_scale_f32_16x16x128_f8f6f4 v[38:41], v[84:87], v[172:175], v[38:41], v187, v187 op_sel_hi:[0,0,0] cbsz:4 blgp:4
	v_mfma_scale_f32_16x16x128_f8f6f4 v[42:45], v[92:95], v[172:175], v[42:45], v187, v187 op_sel_hi:[0,0,0] cbsz:4 blgp:4
	v_mfma_scale_f32_16x16x128_f8f6f4 v[46:49], v[132:135], v[172:175], v[46:49], v187, v187 op_sel_hi:[0,0,0] cbsz:4 blgp:4
	s_waitcnt vmcnt(16)
	v_mfma_scale_f32_16x16x128_f8f6f4 v[56:59], v[168:171], v[172:175], v[56:59], v187, v187 op_sel_hi:[0,0,0] cbsz:4 blgp:4
	global_load_dwordx4 v[80:83], v[0:1], off offset:640
	global_load_dwordx4 v[84:87], v[0:1], off offset:704
	global_load_dwordx4 v[88:91], v[2:3], off offset:640
	global_load_dwordx4 v[92:95], v[2:3], off offset:704
	global_load_dwordx4 v[128:131], v[4:5], off offset:640
	global_load_dwordx4 v[132:135], v[4:5], off offset:704
	global_load_dwordx4 v[164:167], v[6:7], off offset:640
	global_load_dwordx4 v[168:171], v[6:7], off offset:704
	ds_read_b128 v[172:175], v70 offset:576
	ds_read_b128 v[196:199], v70 offset:512
	s_waitcnt vmcnt(23) lgkmcnt(0)
	v_mfma_scale_f32_16x16x128_f8f6f4 v[22:25], v[96:99], v[196:199], v[22:25], v187, v187 op_sel_hi:[0,0,0] cbsz:4 blgp:4
	s_waitcnt vmcnt(21)
	v_mfma_scale_f32_16x16x128_f8f6f4 v[26:29], v[104:107], v[196:199], v[26:29], v187, v187 op_sel_hi:[0,0,0] cbsz:4 blgp:4
	s_waitcnt vmcnt(19)
	v_mfma_scale_f32_16x16x128_f8f6f4 v[30:33], v[112:115], v[196:199], v[30:33], v187, v187 op_sel_hi:[0,0,0] cbsz:4 blgp:4
	s_waitcnt vmcnt(17)
	v_mfma_scale_f32_16x16x128_f8f6f4 v[34:37], v[120:123], v[196:199], v[34:37], v187, v187 op_sel_hi:[0,0,0] cbsz:4 blgp:4
	v_mfma_scale_f32_16x16x128_f8f6f4 v[22:25], v[100:103], v[172:175], v[22:25], v187, v187 op_sel_hi:[0,0,0] cbsz:4 blgp:4
	v_mfma_scale_f32_16x16x128_f8f6f4 v[26:29], v[108:111], v[172:175], v[26:29], v187, v187 op_sel_hi:[0,0,0] cbsz:4 blgp:4
	v_mfma_scale_f32_16x16x128_f8f6f4 v[30:33], v[116:119], v[172:175], v[30:33], v187, v187 op_sel_hi:[0,0,0] cbsz:4 blgp:4
	s_waitcnt vmcnt(16)
	v_mfma_scale_f32_16x16x128_f8f6f4 v[34:37], v[124:127], v[172:175], v[34:37], v187, v187 op_sel_hi:[0,0,0] cbsz:4 blgp:4
	global_load_dwordx4 v[96:99], v[8:9], off offset:640
	global_load_dwordx4 v[100:103], v[8:9], off offset:704
	global_load_dwordx4 v[104:107], v[10:11], off offset:640
	global_load_dwordx4 v[108:111], v[10:11], off offset:704
	global_load_dwordx4 v[112:115], v[18:19], off offset:640
	global_load_dwordx4 v[116:119], v[18:19], off offset:704
	global_load_dwordx4 v[120:123], v[20:21], off offset:640
	global_load_dwordx4 v[124:127], v[20:21], off offset:704
	s_waitcnt vmcnt(23)
	v_mfma_scale_f32_16x16x128_f8f6f4 v[38:41], v[60:63], v[196:199], v[38:41], v187, v187 op_sel_hi:[0,0,0] cbsz:4 blgp:4
	s_waitcnt vmcnt(21)
	v_mfma_scale_f32_16x16x128_f8f6f4 v[42:45], v[72:75], v[196:199], v[42:45], v187, v187 op_sel_hi:[0,0,0] cbsz:4 blgp:4
	s_waitcnt vmcnt(19)
	v_mfma_scale_f32_16x16x128_f8f6f4 v[46:49], v[136:139], v[196:199], v[46:49], v187, v187 op_sel_hi:[0,0,0] cbsz:4 blgp:4
	s_waitcnt vmcnt(17)
	v_mfma_scale_f32_16x16x128_f8f6f4 v[56:59], v[144:147], v[196:199], v[56:59], v187, v187 op_sel_hi:[0,0,0] cbsz:4 blgp:4
	v_mfma_scale_f32_16x16x128_f8f6f4 v[38:41], v[64:67], v[172:175], v[38:41], v187, v187 op_sel_hi:[0,0,0] cbsz:4 blgp:4
	v_mfma_scale_f32_16x16x128_f8f6f4 v[42:45], v[76:79], v[172:175], v[42:45], v187, v187 op_sel_hi:[0,0,0] cbsz:4 blgp:4
	v_mfma_scale_f32_16x16x128_f8f6f4 v[46:49], v[140:143], v[172:175], v[46:49], v187, v187 op_sel_hi:[0,0,0] cbsz:4 blgp:4
	s_waitcnt vmcnt(16)
	v_mfma_scale_f32_16x16x128_f8f6f4 v[56:59], v[160:163], v[172:175], v[56:59], v187, v187 op_sel_hi:[0,0,0] cbsz:4 blgp:4
	global_load_dwordx4 v[60:63], v[0:1], off offset:768
	global_load_dwordx4 v[64:67], v[0:1], off offset:832
	global_load_dwordx4 v[72:75], v[2:3], off offset:768
	global_load_dwordx4 v[76:79], v[2:3], off offset:832
	global_load_dwordx4 v[136:139], v[4:5], off offset:768
	global_load_dwordx4 v[140:143], v[4:5], off offset:832
	global_load_dwordx4 v[144:147], v[6:7], off offset:768
	global_load_dwordx4 v[160:163], v[6:7], off offset:832
	ds_read_b128 v[172:175], v70 offset:704
	ds_read_b128 v[196:199], v70 offset:640
	s_waitcnt vmcnt(23) lgkmcnt(0)
	v_mfma_scale_f32_16x16x128_f8f6f4 v[22:25], v[80:83], v[196:199], v[22:25], v187, v187 op_sel_hi:[0,0,0] cbsz:4 blgp:4
	s_waitcnt vmcnt(21)
	v_mfma_scale_f32_16x16x128_f8f6f4 v[26:29], v[88:91], v[196:199], v[26:29], v187, v187 op_sel_hi:[0,0,0] cbsz:4 blgp:4
	s_waitcnt vmcnt(19)
	v_mfma_scale_f32_16x16x128_f8f6f4 v[30:33], v[128:131], v[196:199], v[30:33], v187, v187 op_sel_hi:[0,0,0] cbsz:4 blgp:4
	s_waitcnt vmcnt(17)
	v_mfma_scale_f32_16x16x128_f8f6f4 v[34:37], v[164:167], v[196:199], v[34:37], v187, v187 op_sel_hi:[0,0,0] cbsz:4 blgp:4
	v_mfma_scale_f32_16x16x128_f8f6f4 v[22:25], v[84:87], v[172:175], v[22:25], v187, v187 op_sel_hi:[0,0,0] cbsz:4 blgp:4
	v_mfma_scale_f32_16x16x128_f8f6f4 v[26:29], v[92:95], v[172:175], v[26:29], v187, v187 op_sel_hi:[0,0,0] cbsz:4 blgp:4
	v_mfma_scale_f32_16x16x128_f8f6f4 v[30:33], v[132:135], v[172:175], v[30:33], v187, v187 op_sel_hi:[0,0,0] cbsz:4 blgp:4
	s_waitcnt vmcnt(16)
	v_mfma_scale_f32_16x16x128_f8f6f4 v[34:37], v[168:171], v[172:175], v[34:37], v187, v187 op_sel_hi:[0,0,0] cbsz:4 blgp:4
	global_load_dwordx4 v[80:83], v[8:9], off offset:768
	global_load_dwordx4 v[84:87], v[8:9], off offset:832
	global_load_dwordx4 v[88:91], v[10:11], off offset:768
	global_load_dwordx4 v[92:95], v[10:11], off offset:832
	global_load_dwordx4 v[128:131], v[18:19], off offset:768
	global_load_dwordx4 v[132:135], v[18:19], off offset:832
	global_load_dwordx4 v[164:167], v[20:21], off offset:768
	global_load_dwordx4 v[168:171], v[20:21], off offset:832
	s_waitcnt vmcnt(23)
	v_mfma_scale_f32_16x16x128_f8f6f4 v[38:41], v[96:99], v[196:199], v[38:41], v187, v187 op_sel_hi:[0,0,0] cbsz:4 blgp:4
	s_waitcnt vmcnt(21)
	v_mfma_scale_f32_16x16x128_f8f6f4 v[42:45], v[104:107], v[196:199], v[42:45], v187, v187 op_sel_hi:[0,0,0] cbsz:4 blgp:4
	s_waitcnt vmcnt(19)
	v_mfma_scale_f32_16x16x128_f8f6f4 v[46:49], v[112:115], v[196:199], v[46:49], v187, v187 op_sel_hi:[0,0,0] cbsz:4 blgp:4
	s_waitcnt vmcnt(17)
	v_mfma_scale_f32_16x16x128_f8f6f4 v[56:59], v[120:123], v[196:199], v[56:59], v187, v187 op_sel_hi:[0,0,0] cbsz:4 blgp:4
	v_mfma_scale_f32_16x16x128_f8f6f4 v[38:41], v[100:103], v[172:175], v[38:41], v187, v187 op_sel_hi:[0,0,0] cbsz:4 blgp:4
	v_mfma_scale_f32_16x16x128_f8f6f4 v[42:45], v[108:111], v[172:175], v[42:45], v187, v187 op_sel_hi:[0,0,0] cbsz:4 blgp:4
	v_mfma_scale_f32_16x16x128_f8f6f4 v[46:49], v[116:119], v[172:175], v[46:49], v187, v187 op_sel_hi:[0,0,0] cbsz:4 blgp:4
	s_waitcnt vmcnt(16)
	v_mfma_scale_f32_16x16x128_f8f6f4 v[56:59], v[124:127], v[172:175], v[56:59], v187, v187 op_sel_hi:[0,0,0] cbsz:4 blgp:4
	global_load_dwordx4 v[96:99], v[0:1], off offset:896
	global_load_dwordx4 v[100:103], v[0:1], off offset:960
	global_load_dwordx4 v[104:107], v[2:3], off offset:896
	global_load_dwordx4 v[108:111], v[2:3], off offset:960
	global_load_dwordx4 v[112:115], v[4:5], off offset:896
	global_load_dwordx4 v[116:119], v[4:5], off offset:960
	global_load_dwordx4 v[120:123], v[6:7], off offset:896
	global_load_dwordx4 v[124:127], v[6:7], off offset:960
	ds_read_b128 v[0:3], v70 offset:832
	ds_read_b128 v[4:7], v70 offset:768
	s_waitcnt vmcnt(23) lgkmcnt(0)
	v_mfma_scale_f32_16x16x128_f8f6f4 v[22:25], v[60:63], v[4:7], v[22:25], v187, v187 op_sel_hi:[0,0,0] cbsz:4 blgp:4
	s_waitcnt vmcnt(22)
	v_mfma_scale_f32_16x16x128_f8f6f4 v[172:175], v[64:67], v[0:3], v[22:25], v187, v187 op_sel_hi:[0,0,0] cbsz:4 blgp:4
	s_waitcnt vmcnt(21)
	v_mfma_scale_f32_16x16x128_f8f6f4 v[22:25], v[72:75], v[4:7], v[26:29], v187, v187 op_sel_hi:[0,0,0] cbsz:4 blgp:4
	s_waitcnt vmcnt(20)
	v_mfma_scale_f32_16x16x128_f8f6f4 v[72:75], v[76:79], v[0:3], v[22:25], v187, v187 op_sel_hi:[0,0,0] cbsz:4 blgp:4
	s_waitcnt vmcnt(19)
	v_mfma_scale_f32_16x16x128_f8f6f4 v[22:25], v[136:139], v[4:7], v[30:33], v187, v187 op_sel_hi:[0,0,0] cbsz:4 blgp:4
	s_waitcnt vmcnt(18)
	v_mfma_scale_f32_16x16x128_f8f6f4 v[76:79], v[140:143], v[0:3], v[22:25], v187, v187 op_sel_hi:[0,0,0] cbsz:4 blgp:4
	s_waitcnt vmcnt(17)
	v_mfma_scale_f32_16x16x128_f8f6f4 v[22:25], v[144:147], v[4:7], v[34:37], v187, v187 op_sel_hi:[0,0,0] cbsz:4 blgp:4
	s_waitcnt vmcnt(16)
	v_mfma_scale_f32_16x16x128_f8f6f4 v[160:163], v[160:163], v[0:3], v[22:25], v187, v187 op_sel_hi:[0,0,0] cbsz:4 blgp:4
	global_load_dwordx4 v[196:199], v[8:9], off offset:896
	global_load_dwordx4 v[200:203], v[8:9], off offset:960
	global_load_dwordx4 v[204:207], v[10:11], off offset:896
	global_load_dwordx4 v[208:211], v[10:11], off offset:960
	global_load_dwordx4 v[226:229], v[18:19], off offset:896
	global_load_dwordx4 v[230:233], v[18:19], off offset:960
	global_load_dwordx4 v[234:237], v[20:21], off offset:896
	global_load_dwordx4 v[238:241], v[20:21], off offset:960
	s_waitcnt vmcnt(23)
	v_mfma_scale_f32_16x16x128_f8f6f4 v[8:11], v[80:83], v[4:7], v[38:41], v187, v187 op_sel_hi:[0,0,0] cbsz:4 blgp:4
	s_waitcnt vmcnt(22)
	v_mfma_scale_f32_16x16x128_f8f6f4 v[80:83], v[84:87], v[0:3], v[8:11], v187, v187 op_sel_hi:[0,0,0] cbsz:4 blgp:4
	s_waitcnt vmcnt(21)
	v_mfma_scale_f32_16x16x128_f8f6f4 v[8:11], v[88:91], v[4:7], v[42:45], v187, v187 op_sel_hi:[0,0,0] cbsz:4 blgp:4
	s_waitcnt vmcnt(20)
	v_mfma_scale_f32_16x16x128_f8f6f4 v[84:87], v[92:95], v[0:3], v[8:11], v187, v187 op_sel_hi:[0,0,0] cbsz:4 blgp:4
	s_waitcnt vmcnt(19)
	v_mfma_scale_f32_16x16x128_f8f6f4 v[8:11], v[128:131], v[4:7], v[46:49], v187, v187 op_sel_hi:[0,0,0] cbsz:4 blgp:4
	s_waitcnt vmcnt(17)
	v_mfma_scale_f32_16x16x128_f8f6f4 v[4:7], v[164:167], v[4:7], v[56:59], v187, v187 op_sel_hi:[0,0,0] cbsz:4 blgp:4
	v_mfma_scale_f32_16x16x128_f8f6f4 v[88:91], v[132:135], v[0:3], v[8:11], v187, v187 op_sel_hi:[0,0,0] cbsz:4 blgp:4
	s_waitcnt vmcnt(16)
	v_mfma_scale_f32_16x16x128_f8f6f4 v[92:95], v[168:171], v[0:3], v[4:7], v187, v187 op_sel_hi:[0,0,0] cbsz:4 blgp:4
	v_mov_b32_e32 v0, v52
	v_mov_b32_e32 v1, v16
	v_mov_b32_e32 v22, v53
	v_mov_b32_e32 v23, v16
	v_mov_b32_e32 v38, v54
	v_mov_b32_e32 v39, v16
	v_mov_b32_e32 v54, v55
	v_mov_b32_e32 v55, v16
	v_lshlrev_b64 v[0:1], 10, v[0:1]
	v_lshlrev_b64 v[22:23], 10, v[22:23]
	v_lshlrev_b64 v[38:39], 10, v[38:39]
	v_lshlrev_b64 v[54:55], 10, v[54:55]
	v_lshl_add_u64 v[18:19], v[182:183], 0, v[0:1]
	v_lshl_add_u64 v[34:35], v[182:183], 0, v[22:23]
	v_lshl_add_u64 v[50:51], v[182:183], 0, v[38:39]
	v_lshl_add_u64 v[66:67], v[182:183], 0, v[54:55]
	global_load_dwordx4 v[0:3], v[18:19], off
	global_load_dwordx4 v[4:7], v[18:19], off offset:256
	global_load_dwordx4 v[8:11], v[18:19], off offset:512
	s_nop 0
	global_load_dwordx4 v[18:21], v[18:19], off offset:768
	s_nop 0
	global_load_dwordx4 v[22:25], v[34:35], off
	global_load_dwordx4 v[26:29], v[34:35], off offset:256
	global_load_dwordx4 v[30:33], v[34:35], off offset:512
	s_nop 0
	global_load_dwordx4 v[34:37], v[34:35], off offset:768
	s_nop 0
	global_load_dwordx4 v[38:41], v[50:51], off
	global_load_dwordx4 v[42:45], v[50:51], off offset:256
	global_load_dwordx4 v[46:49], v[50:51], off offset:512
	s_nop 0
	global_load_dwordx4 v[50:53], v[50:51], off offset:768
	s_nop 0
	global_load_dwordx4 v[54:57], v[66:67], off
	global_load_dwordx4 v[58:61], v[66:67], off offset:256
	global_load_dwordx4 v[62:65], v[66:67], off offset:512
	s_nop 0
	global_load_dwordx4 v[66:69], v[66:67], off offset:768
	ds_read_b128 v[164:167], v70 offset:960
	ds_read_b128 v[168:171], v70 offset:896
	s_waitcnt vmcnt(29) lgkmcnt(0)
	v_mfma_scale_f32_16x16x128_f8f6f4 v[70:73], v[104:107], v[168:171], v[72:75], v187, v187 op_sel_hi:[0,0,0] cbsz:4 blgp:4
	s_waitcnt vmcnt(28)
	v_mfma_scale_f32_16x16x128_f8f6f4 v[142:145], v[108:111], v[164:167], v[70:73], v187, v187 op_sel_hi:[0,0,0] cbsz:4 blgp:4
	s_waitcnt vmcnt(27)
	v_mfma_scale_f32_16x16x128_f8f6f4 v[70:73], v[112:115], v[168:171], v[76:79], v187, v187 op_sel_hi:[0,0,0] cbsz:4 blgp:4
	v_mfma_scale_f32_16x16x128_f8f6f4 v[96:99], v[96:99], v[168:171], v[172:175], v187, v187 op_sel_hi:[0,0,0] cbsz:4 blgp:4
	s_waitcnt vmcnt(26)
	v_mfma_scale_f32_16x16x128_f8f6f4 v[138:141], v[116:119], v[164:167], v[70:73], v187, v187 op_sel_hi:[0,0,0] cbsz:4 blgp:4
	s_waitcnt vmcnt(25)
	v_mfma_scale_f32_16x16x128_f8f6f4 v[70:73], v[120:123], v[168:171], v[160:163], v187, v187 op_sel_hi:[0,0,0] cbsz:4 blgp:4
	v_mfma_scale_f32_16x16x128_f8f6f4 v[146:149], v[100:103], v[164:167], v[96:99], v187, v187 op_sel_hi:[0,0,0] cbsz:4 blgp:4
	s_waitcnt vmcnt(24)
	v_mfma_scale_f32_16x16x128_f8f6f4 v[134:137], v[124:127], v[164:167], v[70:73], v187, v187 op_sel_hi:[0,0,0] cbsz:4 blgp:4
	s_waitcnt vmcnt(23)
	v_mfma_scale_f32_16x16x128_f8f6f4 v[70:73], v[196:199], v[168:171], v[80:83], v187, v187 op_sel_hi:[0,0,0] cbsz:4 blgp:4
	s_waitcnt vmcnt(22)
	v_mfma_scale_f32_16x16x128_f8f6f4 v[130:133], v[200:203], v[164:167], v[70:73], v187, v187 op_sel_hi:[0,0,0] cbsz:4 blgp:4
	s_waitcnt vmcnt(21)
	v_mfma_scale_f32_16x16x128_f8f6f4 v[70:73], v[204:207], v[168:171], v[84:87], v187, v187 op_sel_hi:[0,0,0] cbsz:4 blgp:4
	s_waitcnt vmcnt(20)
	v_mfma_scale_f32_16x16x128_f8f6f4 v[126:129], v[208:211], v[164:167], v[70:73], v187, v187 op_sel_hi:[0,0,0] cbsz:4 blgp:4
	s_waitcnt vmcnt(19)
	v_mfma_scale_f32_16x16x128_f8f6f4 v[70:73], v[226:229], v[168:171], v[88:91], v187, v187 op_sel_hi:[0,0,0] cbsz:4 blgp:4
	s_waitcnt vmcnt(18)
	v_mfma_scale_f32_16x16x128_f8f6f4 v[122:125], v[230:233], v[164:167], v[70:73], v187, v187 op_sel_hi:[0,0,0] cbsz:4 blgp:4
	s_waitcnt vmcnt(17)
	v_mfma_scale_f32_16x16x128_f8f6f4 v[70:73], v[234:237], v[168:171], v[92:95], v187, v187 op_sel_hi:[0,0,0] cbsz:4 blgp:4
	s_waitcnt vmcnt(16)
	v_mfma_scale_f32_16x16x128_f8f6f4 v[118:121], v[238:241], v[164:167], v[70:73], v187, v187 op_sel_hi:[0,0,0] cbsz:4 blgp:4
	s_nop 5
	v_mov_b32_e32 v70, v12
	v_mov_b32_e32 v71, v16
	v_mov_b32_e32 v12, v13
	v_mov_b32_e32 v13, v16
	v_lshlrev_b64 v[70:71], 10, v[70:71]
	v_lshlrev_b64 v[12:13], 10, v[12:13]
	v_lshl_add_u64 v[82:83], v[182:183], 0, v[70:71]
	v_lshl_add_u64 v[12:13], v[182:183], 0, v[12:13]
	global_load_dwordx4 v[70:73], v[82:83], off
	global_load_dwordx4 v[74:77], v[82:83], off offset:256
	global_load_dwordx4 v[78:81], v[82:83], off offset:512
	s_nop 0
	global_load_dwordx4 v[82:85], v[82:83], off offset:768
	s_nop 0
	global_load_dwordx4 v[86:89], v[12:13], off
	global_load_dwordx4 v[90:93], v[12:13], off offset:256
	global_load_dwordx4 v[94:97], v[12:13], off offset:512
	global_load_dwordx4 v[98:101], v[12:13], off offset:768
	v_mov_b32_e32 v12, v14
	v_mov_b32_e32 v13, v16
	v_lshlrev_b64 v[12:13], 10, v[12:13]
	v_lshl_add_u64 v[12:13], v[182:183], 0, v[12:13]
	global_load_dwordx4 v[102:105], v[12:13], off
	global_load_dwordx4 v[106:109], v[12:13], off offset:256
	global_load_dwordx4 v[110:113], v[12:13], off offset:512
	global_load_dwordx4 v[114:117], v[12:13], off offset:768
	v_cmp_lt_i32_e32 vcc, 0, v154
	v_mov_b32_e32 v12, 0x3d321643
	s_and_saveexec_b64 s[10:11], vcc
	s_cbranch_execz .LBB0_738
	v_cmp_ne_u32_e32 vcc, 1, v154
	s_and_saveexec_b64 s[12:13], vcc
	s_xor_b64 s[12:13], exec, s[12:13]
	v_cmp_eq_u32_e32 vcc, 2, v154
	v_mov_b32_e32 v12, 0x3a321643
	v_mov_b32_e32 v13, 0x3b321643
	v_cndmask_b32_e32 v12, v12, v13, vcc
	s_andn2_saveexec_b64 s[12:13], s[12:13]
	v_mov_b32_e32 v12, 0x3c321643
	s_or_b64 exec, exec, s[12:13]
